# combine phase: the 4 wide loads (a0,a1,a2,zz) issued before waiting on the 3 lse loads; softmax-weight math moved after on renamed temporaries (4 -> 3 round trips per pass, 7 loads in flight)
# speedup vs baseline: 1.0140x; 1.0140x over previous
; __device__ __forceinline__ unsigned pk2(float lo, float hi) { unsigned r; asm("v_cvt_pk_bf16_f32 %0, %1, %2" : "=v"(r) : "v"(lo), "v"(hi)); return r; }
; __device__ __forceinline__ float bf_lo(unsigned u) { return __uint_as_float(u << 16); }
; __device__ __forceinline__ float bf_hi(unsigned u) { return __uint_as_float(u & 0xffff0000u); }
; __device__ __forceinline__ float fexp2(float x) { return __builtin_amdgcn_exp2f(x); }
; __device__ __forceinline__ void phase_combine(const Params& P, int layer_i) {
;     ...
;             const int pos = s0 + pass * 32 + (tid2 >> 4); const size_t row = (size_t)b * SEQ + pos;
;             const float l0 = Lse[row * 8 + hh], l1 = Lse[(size_t)MTOK * 8 + row * 8 + hh], l2 = Lse[(size_t)2 * MTOK * 8 + row * 8 + hh];
;             const float lm = fmaxf(l0, fmaxf(l1, l2));
;             float e0 = fexp2((l0 - lm) * 1.4426950408889634f), e1 = fexp2((l1 - lm) * 1.4426950408889634f), e2 = fexp2((l2 - lm) * 1.4426950408889634f);
;             const float ei = 1.f / (e0 + e1 + e2); e0 *= ei; e1 *= ei; e2 *= ei;
;             const u32x4 a0 = *(const u32x4*)(Op + row * AW + col), a1 = *(const u32x4*)(Op + (size_t)MTOK * AW + row * AW + col), a2 = *(const u32x4*)(Op + (size_t)2 * MTOK * AW + row * AW + col);
;             const u32x4 zz = *(const u32x4*)(sza + row * AW + col);
;             u32x4 ya;
; #pragma unroll
;             for (int e = 0; e < 4; ++e) {
;                 const float lo = (e0 * bf_lo(a0[e]) + e1 * bf_lo(a1[e]) + e2 * bf_lo(a2[e])) * bf_lo(zz[e]);
;                 const float hi = (e0 * bf_hi(a0[e]) + e1 * bf_hi(a1[e]) + e2 * bf_hi(a2[e])) * bf_hi(zz[e]);
;                 ya[e] = pk2(lo, hi); }
;             *(u32x4*)(Y + row * DM + col) = ya;
;             const u32x4 pc = *(const u32x4*)(pp + row * AW + col);
;             u32x4 pm = (u32x4){0u, 0u, 0u, 0u}, pn = (u32x4){0u, 0u, 0u, 0u};
;             if (pos > 0) pm = *(const u32x4*)(pp + (row - 1) * AW + col);
;             if (pos < SEQ - 1) pn = *(const u32x4*)(pp + (row + 1) * AW + col);
.LBB0_255:
	s_nop 0
	v_lshl_add_u64 v[18:19], s[12:13], 0, v[46:47]
	v_add_co_u32_e32 v20, vcc, 0x1f6e4000, v18
	v_lshl_add_u64 v[56:57], s[12:13], 0, v[42:43]
	s_nop 0
	v_addc_co_u32_e32 v21, vcc, 0, v19, vcc
	global_load_dword v79, v[20:21], off
	v_add_co_u32_e32 v20, vcc, 0x1f764000, v18
	v_add_u32_e32 v0, s6, v34
	s_nop 0
	v_addc_co_u32_e32 v21, vcc, 0, v19, vcc
	v_add_co_u32_e32 v18, vcc, 0x1f7e4000, v18
	global_load_dword v77, v[20:21], off
	s_nop 0
	v_addc_co_u32_e32 v19, vcc, 0, v19, vcc
	global_load_dword v75, v[18:19], off
	v_add_co_u32_e32 v18, vcc, s79, v56
	s_nop 0
	v_addc_co_u32_e32 v19, vcc, 0, v57, vcc
	v_add_co_u32_e32 v22, vcc, s80, v56
	global_load_dwordx4 v[18:21], v[18:19], off
	s_nop 0
	v_addc_co_u32_e32 v23, vcc, 0, v57, vcc
	v_add_co_u32_e32 v26, vcc, s81, v56
	global_load_dwordx4 v[22:25], v[22:23], off
	s_nop 0
	v_addc_co_u32_e32 v27, vcc, 0, v57, vcc
	v_add_co_u32_e32 v30, vcc, s82, v56
	global_load_dwordx4 v[26:29], v[26:27], off
	s_nop 0
	v_addc_co_u32_e32 v31, vcc, 0, v57, vcc
	global_load_dwordx4 v[30:33], v[30:31], off
	s_waitcnt vmcnt(4) lgkmcnt(0)
	v_max3_f32 v76, v79, v77, v75
	v_sub_f32_e32 v78, v79, v76
	v_sub_f32_e32 v77, v77, v76
	v_mul_f32_e32 v78, 0x3fb8aa3b, v78
	v_mul_f32_e32 v77, 0x3fb8aa3b, v77
	v_sub_f32_e32 v75, v75, v76
	v_exp_f32_e32 v59, v78
	v_exp_f32_e32 v77, v77
	v_mul_f32_e32 v75, 0x3fb8aa3b, v75
	v_exp_f32_e32 v58, v75
	v_add_f32_e32 v75, v59, v77
	v_add_f32_e32 v75, v58, v75
	v_div_scale_f32 v76, s[2:3], v75, v75, 1.0
	v_rcp_f32_e32 v78, v76
	s_nop 0
	v_fma_f32 v79, -v76, v78, 1.0
	v_fmac_f32_e32 v78, v79, v78
	v_div_scale_f32 v79, vcc, 1.0, v75, 1.0
	v_mul_f32_e32 v80, v79, v78
	v_fma_f32 v81, -v76, v80, v79
	v_fmac_f32_e32 v80, v81, v78
	v_fma_f32 v76, -v76, v80, v79
	v_div_fmas_f32 v76, v76, v78, v80
	v_div_fixup_f32 v64, v76, v75, 1.0
	v_mul_f32_e32 v35, v77, v64
	s_waitcnt vmcnt(0) lgkmcnt(0)
	v_lshlrev_b32_e32 v63, 16, v22
	v_and_b32_e32 v66, 0xffff0000, v22
	v_lshlrev_b32_e32 v68, 16, v23
	v_and_b32_e32 v70, 0xffff0000, v23
	v_lshlrev_b32_e32 v72, 16, v24
	v_and_b32_e32 v24, 0xffff0000, v24
	v_lshlrev_b32_e32 v74, 16, v25
	v_lshlrev_b32_e32 v65, 16, v30
	v_and_b32_e32 v67, 0xffff0000, v30
	v_lshlrev_b32_e32 v69, 16, v31
	v_and_b32_e32 v71, 0xffff0000, v31
	v_pk_mul_f32 v[22:23], v[58:59], v[64:65] op_sel_hi:[1,0]
	v_lshlrev_b32_e32 v31, 16, v18
	v_lshlrev_b32_e32 v30, 16, v26
	v_pk_mul_f32 v[30:31], v[22:23], v[30:31]
	v_lshlrev_b32_e32 v73, 16, v32
	v_fma_f32 v31, v35, v63, v31
	v_add_f32_e32 v30, v30, v31
	v_mul_f32_e32 v58, v30, v65
	v_and_b32_e32 v31, 0xffff0000, v18
	v_and_b32_e32 v30, 0xffff0000, v26
	v_pk_mul_f32 v[30:31], v[22:23], v[30:31]
	v_and_b32_e32 v32, 0xffff0000, v32
	v_fma_f32 v18, v35, v66, v31
	v_add_f32_e32 v18, v30, v18
	v_lshlrev_b32_e32 v31, 16, v19
	v_lshlrev_b32_e32 v30, 16, v27
	v_pk_mul_f32 v[30:31], v[22:23], v[30:31]
	v_mul_f32_e32 v18, v18, v67
	v_fma_f32 v26, v35, v68, v31
	v_add_f32_e32 v26, v30, v26
	v_and_b32_e32 v31, 0xffff0000, v19
	v_and_b32_e32 v30, 0xffff0000, v27
	v_cvt_pk_bf16_f32 v18, v58, v18
	v_mul_f32_e32 v58, v26, v69
	v_pk_mul_f32 v[26:27], v[22:23], v[30:31]
	s_nop 0
	v_fma_f32 v19, v35, v70, v27
	v_add_f32_e32 v19, v26, v19
	v_lshlrev_b32_e32 v27, 16, v20
	v_lshlrev_b32_e32 v26, 16, v28
	v_pk_mul_f32 v[26:27], v[22:23], v[26:27]
	v_mul_f32_e32 v19, v19, v71
	v_fma_f32 v27, v35, v72, v27
	v_add_f32_e32 v26, v26, v27
	v_mul_f32_e32 v30, v26, v73
	v_and_b32_e32 v27, 0xffff0000, v20
	v_and_b32_e32 v26, 0xffff0000, v28
	v_pk_mul_f32 v[26:27], v[22:23], v[26:27]
	v_cvt_pk_bf16_f32 v19, v58, v19
	v_mov_b32_e32 v28, 0
	v_fma_f32 v20, v35, v24, v27
	v_add_f32_e32 v20, v26, v20
	v_lshlrev_b32_e32 v27, 16, v21
	v_lshlrev_b32_e32 v26, 16, v29
	v_pk_mul_f32 v[26:27], v[22:23], v[26:27]
	v_mul_f32_e32 v20, v20, v32
	v_fma_f32 v24, v35, v74, v27
	v_add_f32_e32 v24, v26, v24
	v_lshlrev_b32_e32 v26, 16, v33
	v_mul_f32_e32 v26, v24, v26
	v_and_b32_e32 v27, 0xffff0000, v25
	v_and_b32_e32 v25, 0xffff0000, v21
	v_and_b32_e32 v24, 0xffff0000, v29
	v_pk_mul_f32 v[22:23], v[22:23], v[24:25]
	v_cvt_pk_bf16_f32 v20, v30, v20
	v_lshl_add_u64 v[30:31], s[12:13], 0, v[44:45]
	v_fma_f32 v21, v35, v27, v23
	v_add_f32_e32 v21, v22, v21
	v_and_b32_e32 v22, 0xffff0000, v33
	v_mul_f32_e32 v21, v21, v22
	v_add_co_u32_e32 v22, vcc, 0x96e4000, v30
	v_cvt_pk_bf16_f32 v21, v26, v21
	v_mov_b32_e32 v26, 0
	s_nop 0
	v_addc_co_u32_e32 v23, vcc, 0, v31, vcc
	global_store_dwordx4 v[22:23], v[18:21], off
	v_mov_b32_e32 v22, 0
	v_mov_b32_e32 v27, 0
	v_add_co_u32_e32 v18, vcc, 0x156e4000, v56
	v_mov_b32_e32 v29, 0
	s_nop 0
	v_addc_co_u32_e32 v19, vcc, 0, v57, vcc
	global_load_dwordx4 v[18:21], v[18:19], off
	v_cmp_lt_i32_e32 vcc, 0, v0
	s_and_saveexec_b64 s[24:25], vcc
	s_cbranch_execz .LBB0_257
	v_add_co_u32_e32 v24, vcc, 0x156e3000, v56
	s_nop 1
	v_addc_co_u32_e32 v25, vcc, 0, v57, vcc
	global_load_dwordx4 v[26:29], v[24:25], off offset:2048

; __device__ __forceinline__ unsigned pk2(float lo, float hi) { unsigned r; asm("v_cvt_pk_bf16_f32 %0, %1, %2" : "=v"(r) : "v"(lo), "v"(hi)); return r; }
; __device__ __forceinline__ float bf_lo(unsigned u) { return __uint_as_float(u << 16); }
; __device__ __forceinline__ float bf_hi(unsigned u) { return __uint_as_float(u & 0xffff0000u); }
; __device__ __forceinline__ float fexp2(float x) { return __builtin_amdgcn_exp2f(x); }
; __device__ __forceinline__ void phase_combine(const Params& P, int layer_i) {
;     ...
;             const int pos = s0 + pass * 32 + (tid2 >> 4); const size_t row = (size_t)b * SEQ + pos;
;             const float l0 = Lse[row * 8 + hh], l1 = Lse[(size_t)MTOK * 8 + row * 8 + hh], l2 = Lse[(size_t)2 * MTOK * 8 + row * 8 + hh];
;             const float lm = fmaxf(l0, fmaxf(l1, l2));
;             float e0 = fexp2((l0 - lm) * 1.4426950408889634f), e1 = fexp2((l1 - lm) * 1.4426950408889634f), e2 = fexp2((l2 - lm) * 1.4426950408889634f);
;             const float ei = 1.f / (e0 + e1 + e2); e0 *= ei; e1 *= ei; e2 *= ei;
;             const u32x4 a0 = *(const u32x4*)(Op + row * AW + col), a1 = *(const u32x4*)(Op + (size_t)MTOK * AW + row * AW + col), a2 = *(const u32x4*)(Op + (size_t)2 * MTOK * AW + row * AW + col);
;             const u32x4 zz = *(const u32x4*)(sza + row * AW + col);
;     ...
;             const u32x4 gg = *(const u32x4*)(gz + row * AW + col);
;             u32x4 yb;
; #pragma unroll
;             for (int e = 0; e < 4; ++e) {
;                 const float lo = bf_lo(gg[e]) * (w0[2 * e] * bf_lo(pm[e]) + w1[2 * e] * bf_lo(pc[e]) + w2[2 * e] * bf_lo(pn[e]));
;                 const float hi = bf_hi(gg[e]) * (w0[2 * e + 1] * bf_hi(pm[e]) + w1[2 * e + 1] * bf_hi(pc[e]) + w2[2 * e + 1] * bf_hi(pn[e]));
;                 yb[e] = pk2(lo, hi); }
;             *(u32x4*)(Y + row * DM + AW + col) = yb;
.LBB0_259:
	s_or_b64 exec, exec, s[24:25]
	v_add_co_u32_e32 v32, vcc, 0x176e4000, v56
	s_waitcnt vmcnt(0) lgkmcnt(0)
	v_lshlrev_b32_e32 v63, 16, v26
	v_addc_co_u32_e32 v33, vcc, 0, v57, vcc
	global_load_dwordx4 v[56:59], v[32:33], off
	v_lshlrev_b32_e32 v33, 16, v22
	v_lshlrev_b32_e32 v32, 16, v18
	v_pk_mul_f32 v[32:33], v[54:55], v[32:33]
	v_and_b32_e32 v26, 0xffff0000, v26
	v_fma_f32 v32, v10, v63, v32
	v_add_f32_e32 v32, v32, v33
	v_and_b32_e32 v33, 0xffff0000, v22
	s_mov_b32 s2, 0x1f6e4000
	v_add_u32_e32 v0, 32, v0
	s_waitcnt vmcnt(0) lgkmcnt(0)
	v_lshlrev_b32_e32 v35, 16, v56
	v_mul_f32_e32 v35, v32, v35
	v_and_b32_e32 v32, 0xffff0000, v18
	v_pk_mul_f32 v[32:33], v[6:7], v[32:33]
	v_lshlrev_b32_e32 v22, 16, v57
	v_fma_f32 v18, v11, v26, v32
	v_add_f32_e32 v18, v18, v33
	v_lshlrev_b32_e32 v33, 16, v23
	v_lshlrev_b32_e32 v32, 16, v19
	v_lshlrev_b32_e32 v26, 16, v27
	v_pk_mul_f32 v[32:33], v[52:53], v[32:33]
	v_and_b32_e32 v23, 0xffff0000, v23
	v_fma_f32 v26, v12, v26, v32
	v_add_f32_e32 v26, v26, v33
	v_mul_f32_e32 v26, v26, v22
	v_and_b32_e32 v22, 0xffff0000, v19
	v_and_b32_e32 v27, 0xffff0000, v27
	v_pk_mul_f32 v[22:23], v[8:9], v[22:23]
	v_and_b32_e32 v32, 0xffff0000, v57
	v_fma_f32 v19, v13, v27, v22
	v_add_f32_e32 v19, v19, v23
	v_lshlrev_b32_e32 v23, 16, v24
	v_lshlrev_b32_e32 v22, 16, v20
	v_lshlrev_b32_e32 v27, 16, v28
	v_pk_mul_f32 v[22:23], v[50:51], v[22:23]
	v_mul_f32_e32 v19, v19, v32
	v_fma_f32 v22, v14, v27, v22
	v_cvt_pk_bf16_f32 v19, v26, v19
	v_lshlrev_b32_e32 v26, 16, v58
	v_add_f32_e32 v22, v22, v23
	v_mul_f32_e32 v26, v22, v26
	v_and_b32_e32 v23, 0xffff0000, v24
	v_and_b32_e32 v22, 0xffff0000, v20
	v_and_b32_e32 v28, 0xffff0000, v28
	v_pk_mul_f32 v[22:23], v[2:3], v[22:23]
	v_and_b32_e32 v27, 0xffff0000, v58
	v_fma_f32 v20, v15, v28, v22
	v_add_f32_e32 v20, v20, v23
	v_mul_f32_e32 v20, v20, v27
	v_lshlrev_b32_e32 v23, 16, v25
	v_lshlrev_b32_e32 v22, 16, v21
	v_cvt_pk_bf16_f32 v20, v26, v20
	v_lshlrev_b32_e32 v26, 16, v29
	v_pk_mul_f32 v[22:23], v[48:49], v[22:23]
	v_lshlrev_b32_e32 v24, 16, v59
	v_fma_f32 v22, v16, v26, v22
	v_add_f32_e32 v22, v22, v23
	v_mul_f32_e32 v24, v22, v24
	v_and_b32_e32 v23, 0xffff0000, v25
	v_and_b32_e32 v22, 0xffff0000, v21
	v_and_b32_e32 v27, 0xffff0000, v29
	v_pk_mul_f32 v[22:23], v[4:5], v[22:23]
	v_and_b32_e32 v56, 0xffff0000, v56
	v_fma_f32 v21, v17, v27, v22
	v_mul_f32_e32 v18, v18, v56
	v_and_b32_e32 v26, 0xffff0000, v59
	v_add_f32_e32 v21, v21, v23
	v_add_co_u32_e32 v22, vcc, s83, v30
	v_cvt_pk_bf16_f32 v18, v35, v18
	v_mul_f32_e32 v21, v21, v26
	s_nop 0
	v_addc_co_u32_e32 v23, vcc, 0, v31, vcc
	v_cvt_pk_bf16_f32 v21, v24, v21
	global_store_dwordx4 v[22:23], v[18:21], off offset:2048
	v_lshl_add_u64 v[56:57], s[12:13], 0, v[36:37]
	s_nop 0
	v_lshl_add_u64 v[18:19], s[12:13], 0, v[40:41]
	v_add_co_u32_e32 v20, vcc, s2, v18
	s_mov_b32 s2, 0x1f764000
	s_nop 0
	v_addc_co_u32_e32 v21, vcc, 0, v19, vcc
	global_load_dword v79, v[20:21], off
	v_add_co_u32_e32 v20, vcc, s2, v18
	s_mov_b32 s2, 0x1f7e4000
	s_nop 0
	v_addc_co_u32_e32 v21, vcc, 0, v19, vcc
	v_add_co_u32_e32 v18, vcc, s2, v18
	global_load_dword v77, v[20:21], off
	s_nop 0
	v_addc_co_u32_e32 v19, vcc, 0, v19, vcc
	global_load_dword v75, v[18:19], off
	v_add_co_u32_e32 v18, vcc, s79, v56
	s_nop 0
	v_addc_co_u32_e32 v19, vcc, 0, v57, vcc
	v_add_co_u32_e32 v22, vcc, s80, v56
	global_load_dwordx4 v[18:21], v[18:19], off
	s_nop 0
	v_addc_co_u32_e32 v23, vcc, 0, v57, vcc
	v_add_co_u32_e32 v26, vcc, s81, v56
	global_load_dwordx4 v[22:25], v[22:23], off
	s_nop 0
	v_addc_co_u32_e32 v27, vcc, 0, v57, vcc
	v_add_co_u32_e32 v30, vcc, s82, v56
	global_load_dwordx4 v[26:29], v[26:27], off
	s_nop 0
	v_addc_co_u32_e32 v31, vcc, 0, v57, vcc
	global_load_dwordx4 v[30:33], v[30:31], off
	s_waitcnt vmcnt(4) lgkmcnt(0)
; __device__ __forceinline__ unsigned pk2(float lo, float hi) { unsigned r; asm("v_cvt_pk_bf16_f32 %0, %1, %2" : "=v"(r) : "v"(lo), "v"(hi)); return r; }
; __device__ __forceinline__ float bf_lo(unsigned u) { return __uint_as_float(u << 16); }
; __device__ __forceinline__ float bf_hi(unsigned u) { return __uint_as_float(u & 0xffff0000u); }
; __device__ __forceinline__ float fexp2(float x) { return __builtin_amdgcn_exp2f(x); }
; __device__ __forceinline__ void phase_combine(const Params& P, int layer_i) {
;     ...
;             const float l0 = Lse[row * 8 + hh], l1 = Lse[(size_t)MTOK * 8 + row * 8 + hh], l2 = Lse[(size_t)2 * MTOK * 8 + row * 8 + hh];
;             const float lm = fmaxf(l0, fmaxf(l1, l2));
;             float e0 = fexp2((l0 - lm) * 1.4426950408889634f), e1 = fexp2((l1 - lm) * 1.4426950408889634f), e2 = fexp2((l2 - lm) * 1.4426950408889634f);
;             const float ei = 1.f / (e0 + e1 + e2); e0 *= ei; e1 *= ei; e2 *= ei;
;             const u32x4 a0 = *(const u32x4*)(Op + row * AW + col), a1 = *(const u32x4*)(Op + (size_t)MTOK * AW + row * AW + col), a2 = *(const u32x4*)(Op + (size_t)2 * MTOK * AW + row * AW + col);
;             const u32x4 zz = *(const u32x4*)(sza + row * AW + col);
;             u32x4 ya;
; #pragma unroll
;             for (int e = 0; e < 4; ++e) {
;                 const float lo = (e0 * bf_lo(a0[e]) + e1 * bf_lo(a1[e]) + e2 * bf_lo(a2[e])) * bf_lo(zz[e]);
;                 const float hi = (e0 * bf_hi(a0[e]) + e1 * bf_hi(a1[e]) + e2 * bf_hi(a2[e])) * bf_hi(zz[e]);
;                 ya[e] = pk2(lo, hi); }
;             *(u32x4*)(Y + row * DM + col) = ya;
;             const u32x4 pc = *(const u32x4*)(pp + row * AW + col);
;             u32x4 pm = (u32x4){0u, 0u, 0u, 0u}, pn = (u32x4){0u, 0u, 0u, 0u};
;             if (pos > 0) pm = *(const u32x4*)(pp + (row - 1) * AW + col);
;             if (pos < SEQ - 1) pn = *(const u32x4*)(pp + (row + 1) * AW + col);
	v_max3_f32 v76, v79, v77, v75
	v_sub_f32_e32 v78, v79, v76
	v_sub_f32_e32 v77, v77, v76
	v_mul_f32_e32 v78, 0x3fb8aa3b, v78
	v_mul_f32_e32 v77, 0x3fb8aa3b, v77
	v_sub_f32_e32 v75, v75, v76
	v_exp_f32_e32 v59, v78
	v_exp_f32_e32 v77, v77
	v_mul_f32_e32 v75, 0x3fb8aa3b, v75
	v_exp_f32_e32 v58, v75
	v_add_f32_e32 v75, v59, v77
	v_add_f32_e32 v75, v58, v75
	v_div_scale_f32 v76, s[2:3], v75, v75, 1.0
	v_rcp_f32_e32 v78, v76
	s_nop 0
	v_fma_f32 v79, -v76, v78, 1.0
	v_fmac_f32_e32 v78, v79, v78
	v_div_scale_f32 v79, vcc, 1.0, v75, 1.0
	v_mul_f32_e32 v80, v79, v78
	v_fma_f32 v81, -v76, v80, v79
	v_fmac_f32_e32 v80, v81, v78
	v_fma_f32 v76, -v76, v80, v79
	v_div_fmas_f32 v76, v76, v78, v80
	v_div_fixup_f32 v64, v76, v75, 1.0
	v_mul_f32_e32 v35, v77, v64
	s_waitcnt vmcnt(0) lgkmcnt(0)
	v_lshlrev_b32_e32 v63, 16, v22
	v_and_b32_e32 v66, 0xffff0000, v22
	v_lshlrev_b32_e32 v68, 16, v23
	v_and_b32_e32 v70, 0xffff0000, v23
	v_lshlrev_b32_e32 v72, 16, v24
	v_and_b32_e32 v24, 0xffff0000, v24
	v_lshlrev_b32_e32 v74, 16, v25
	v_lshlrev_b32_e32 v65, 16, v30
	v_and_b32_e32 v67, 0xffff0000, v30
	v_lshlrev_b32_e32 v69, 16, v31
	v_and_b32_e32 v71, 0xffff0000, v31
	v_pk_mul_f32 v[22:23], v[58:59], v[64:65] op_sel_hi:[1,0]
	v_lshlrev_b32_e32 v31, 16, v18
	v_lshlrev_b32_e32 v30, 16, v26
	v_pk_mul_f32 v[30:31], v[22:23], v[30:31]
	v_lshlrev_b32_e32 v73, 16, v32
	v_fma_f32 v31, v35, v63, v31
	v_add_f32_e32 v30, v30, v31
	v_mul_f32_e32 v58, v30, v65
	v_and_b32_e32 v31, 0xffff0000, v18
	v_and_b32_e32 v30, 0xffff0000, v26
	v_pk_mul_f32 v[30:31], v[22:23], v[30:31]
	v_and_b32_e32 v32, 0xffff0000, v32
	v_fma_f32 v18, v35, v66, v31
	v_add_f32_e32 v18, v30, v18
	v_lshlrev_b32_e32 v31, 16, v19
	v_lshlrev_b32_e32 v30, 16, v27
	v_pk_mul_f32 v[30:31], v[22:23], v[30:31]
	v_mul_f32_e32 v18, v18, v67
	v_fma_f32 v26, v35, v68, v31
	v_add_f32_e32 v26, v30, v26
	v_and_b32_e32 v31, 0xffff0000, v19
	v_and_b32_e32 v30, 0xffff0000, v27
	v_cvt_pk_bf16_f32 v18, v58, v18
	v_mul_f32_e32 v58, v26, v69
	v_pk_mul_f32 v[26:27], v[22:23], v[30:31]
	s_nop 0
	v_fma_f32 v19, v35, v70, v27
	v_add_f32_e32 v19, v26, v19
	v_lshlrev_b32_e32 v27, 16, v20
	v_lshlrev_b32_e32 v26, 16, v28
	v_pk_mul_f32 v[26:27], v[22:23], v[26:27]
	v_mul_f32_e32 v19, v19, v71
	v_fma_f32 v27, v35, v72, v27
	v_add_f32_e32 v26, v26, v27
	v_mul_f32_e32 v30, v26, v73
	v_and_b32_e32 v27, 0xffff0000, v20
	v_and_b32_e32 v26, 0xffff0000, v28
	v_pk_mul_f32 v[26:27], v[22:23], v[26:27]
	v_cvt_pk_bf16_f32 v19, v58, v19
	v_mov_b32_e32 v28, 0
	v_fma_f32 v20, v35, v24, v27
	v_add_f32_e32 v20, v26, v20
	v_lshlrev_b32_e32 v27, 16, v21
	v_lshlrev_b32_e32 v26, 16, v29
	v_pk_mul_f32 v[26:27], v[22:23], v[26:27]
	v_mul_f32_e32 v20, v20, v32
	v_fma_f32 v24, v35, v74, v27
	v_add_f32_e32 v24, v26, v24
	v_lshlrev_b32_e32 v26, 16, v33
	v_mul_f32_e32 v26, v24, v26
	v_and_b32_e32 v27, 0xffff0000, v25
	v_and_b32_e32 v25, 0xffff0000, v21
	v_and_b32_e32 v24, 0xffff0000, v29
	v_pk_mul_f32 v[22:23], v[22:23], v[24:25]
	v_cvt_pk_bf16_f32 v20, v30, v20
	v_lshl_add_u64 v[30:31], s[12:13], 0, v[38:39]
	v_fma_f32 v21, v35, v27, v23
	v_add_f32_e32 v21, v22, v21
	v_and_b32_e32 v22, 0xffff0000, v33
	v_mul_f32_e32 v21, v21, v22
	v_add_co_u32_e32 v22, vcc, 0x96e4000, v30
	v_cvt_pk_bf16_f32 v21, v26, v21
	v_mov_b32_e32 v26, 0
	s_nop 0
	v_addc_co_u32_e32 v23, vcc, 0, v31, vcc
	global_store_dwordx4 v[22:23], v[18:21], off
	v_mov_b32_e32 v22, 0
	v_mov_b32_e32 v27, 0
	v_add_co_u32_e32 v18, vcc, 0x156e4000, v56
	v_mov_b32_e32 v29, 0
	s_nop 0
	v_addc_co_u32_e32 v19, vcc, 0, v57, vcc
	global_load_dwordx4 v[18:21], v[18:19], off
	v_cmp_lt_i32_e32 vcc, 0, v0
	s_and_saveexec_b64 s[24:25], vcc
	s_cbranch_execz .LBB0_261
	v_add_co_u32_e32 v24, vcc, 0x156e3000, v56
	s_nop 1
	v_addc_co_u32_e32 v25, vcc, 0, v57, vcc
	global_load_dwordx4 v[26:29], v[24:25], off offset:2048
